# adds: static s_setprio 1 for waves 4-7 during the MLA loop
# speedup vs baseline: 1.0021x; 1.0021x over previous
.LBB0_251:
	s_or_b64 exec, exec, s[2:3]
	v_add_f32_e32 v100, 0, v114
	v_add_f32_e32 v80, 0, v80
	v_add_f32_e32 v100, v115, v100
	v_add_f32_e32 v80, v81, v80
	v_add_f32_e32 v100, v116, v100
	v_add_f32_e32 v80, v82, v80
	v_add_f32_e32 v100, v117, v100
	v_add_f32_e32 v80, v83, v80
	v_add_f32_e32 v100, v118, v100
	v_add_f32_e32 v80, v84, v80
	v_add_f32_e32 v100, v119, v100
	v_add_f32_e32 v80, v85, v80
	v_add_f32_e32 v100, v120, v100
	v_add_f32_e32 v80, v86, v80
	v_add_f32_e32 v100, v121, v100
	v_add_f32_e32 v80, v87, v80
	v_add_f32_e32 v100, v122, v100
	v_add_f32_e32 v80, v88, v80
	v_add_f32_e32 v100, v123, v100
	v_add_f32_e32 v80, v89, v80
	v_add_f32_e32 v100, v124, v100
	v_add_f32_e32 v80, v90, v80
	v_add_f32_e32 v100, v125, v100
	v_add_f32_e32 v80, v91, v80
	v_add_f32_e32 v100, v126, v100
	v_add_f32_e32 v80, v92, v80
	v_add_f32_e32 v100, v127, v100
	v_add_f32_e32 v80, v93, v80
	v_add_f32_e32 v100, v176, v100
	v_add_f32_e32 v80, v94, v80
	v_add_f32_e32 v100, v177, v100
	v_add_f32_e32 v80, v95, v80
	v_add_f32_e32 v100, v178, v100
	v_add_f32_e32 v64, v64, v80
	v_add_f32_e32 v100, v179, v100
	v_add_f32_e32 v64, v65, v64
	v_add_f32_e32 v100, v180, v100
	v_add_f32_e32 v64, v66, v64
	v_add_f32_e32 v100, v181, v100
	v_add_f32_e32 v64, v67, v64
	v_add_f32_e32 v100, v182, v100
	v_add_f32_e32 v64, v68, v64
	v_add_f32_e32 v100, v183, v100
	v_add_f32_e32 v64, v69, v64
	v_add_f32_e32 v100, v184, v100
	v_add_f32_e32 v64, v70, v64
	v_add_f32_e32 v100, v185, v100
	v_add_f32_e32 v64, v71, v64
	v_add_f32_e32 v100, v186, v100
	v_add_f32_e32 v64, v72, v64
	v_add_f32_e32 v100, v187, v100
	v_add_f32_e32 v64, v73, v64
	v_add_f32_e32 v100, v200, v100
	v_add_f32_e32 v64, v74, v64
	v_add_f32_e32 v100, v201, v100
	v_add_f32_e32 v64, v75, v64
	v_add_f32_e32 v100, v202, v100
	v_add_f32_e32 v64, v76, v64
	v_add_f32_e32 v100, v104, v100
	v_add_f32_e32 v64, v77, v64
	v_add_f32_e32 v100, v105, v100
	v_add_f32_e32 v64, v78, v64
	v_mul_u32_u24_e32 v220, 0xd0, v109
	v_mul_u32_u24_e32 v221, 0x90, v109
	v_add_f32_e32 v109, v106, v100
	v_add_f32_e32 v111, v79, v64
	v_pk_add_f32 v[202:203], v[108:109], 0 op_sel_hi:[1,0]
	v_pk_add_f32 v[200:201], v[110:111], 0 op_sel_hi:[1,0]
	v_add_u32_e32 v64, 0x8800, v113
	s_mov_b32 s9, 2
	s_waitcnt vmcnt(0)
	ds_write2_b64 v64, v[96:97], v[98:99] offset0:128 offset1:130
	s_mov_b32 s3, 0
	s_mov_b32 s2, 0x6000
	s_movk_i32 s0, 0x100
	v_lshl_add_u64 v[184:185], v[194:195], 0, s[2:3]
	v_lshl_add_u64 v[180:181], v[196:197], 0, s[2:3]
	v_lshl_add_u64 v[176:177], v[198:199], 0, s[0:1]
	global_load_dwordx4 v[184:187], v[184:185], off
	global_load_dwordx4 v[180:183], v[180:181], off
	global_load_dwordx4 v[176:179], v[176:177], off
	s_movk_i32 s2, 0x5800
	v_add3_u32 v220, v220, v188, s2
	s_movk_i32 s2, 0x3400
	v_add3_u32 v221, v221, v188, s2
	v_add_u32_e32 v238, 0xe000, v219
	v_add_u32_e32 v219, 0x3000, v219
	v_xor_b32_e32 v64, 0x80000000, v202
	v_mov_b32_e32 v65, v64
	v_mov_b32_e32 v66, v64
	v_mov_b32_e32 v67, v64
	v_mov_b32_e32 v68, v64
	v_mov_b32_e32 v69, v64
	v_mov_b32_e32 v70, v64
	v_mov_b32_e32 v71, v64
	v_mov_b32_e32 v72, v64
	v_mov_b32_e32 v73, v64
	v_mov_b32_e32 v74, v64
	v_mov_b32_e32 v75, v64
	v_mov_b32_e32 v76, v64
	v_mov_b32_e32 v77, v64
	v_mov_b32_e32 v78, v64
	v_mov_b32_e32 v79, v64
	v_mov_b32_e32 v96, 0xff800000
	v_mov_b32_e32 v97, 0xff800000
	v_mov_b32_e32 v98, 0xff800000
	v_mov_b32_e32 v99, 0xff800000
	v_mov_b32_e32 v100, 0xff800000
	v_mov_b32_e32 v101, 0xff800000
	v_mov_b32_e32 v102, 0xff800000
	v_mov_b32_e32 v103, 0xff800000
	v_mov_b32_e32 v104, 0xff800000
	v_mov_b32_e32 v105, 0xff800000
	v_mov_b32_e32 v106, 0xff800000
	v_mov_b32_e32 v107, 0xff800000
	v_mov_b32_e32 v108, 0xff800000
	v_mov_b32_e32 v109, 0xff800000
	v_mov_b32_e32 v110, 0xff800000
	v_mov_b32_e32 v111, 0xff800000
	v_mov_b32_e32 v80, 0xff800000
	v_mov_b32_e32 v81, 0xff800000
	v_mov_b32_e32 v82, 0xff800000
	v_mov_b32_e32 v83, 0xff800000
	v_mov_b32_e32 v84, 0xff800000
	v_mov_b32_e32 v85, 0xff800000
	v_mov_b32_e32 v86, 0xff800000
	v_mov_b32_e32 v87, 0xff800000
	v_mov_b32_e32 v88, 0xff800000
	v_mov_b32_e32 v89, 0xff800000
	v_mov_b32_e32 v90, 0xff800000
	v_mov_b32_e32 v91, 0xff800000
	v_mov_b32_e32 v92, 0xff800000
	v_mov_b32_e32 v93, 0xff800000
	v_mov_b32_e32 v94, 0xff800000
	v_mov_b32_e32 v95, 0xff800000
	s_mov_b32 s10, 1
	s_mov_b32 s3, 0
	s_waitcnt vmcnt(0)
	ds_write_b128 v216, v[184:187] offset:45056
	s_and_saveexec_b64 vcc, s[4:5]
	ds_write_b128 v217, v[180:183] offset:45056
	s_mov_b64 exec, vcc
	ds_write2_b64 v238, v[176:177], v[178:179] offset0:128 offset1:130
	s_nop 3
	s_mov_b32 s2, 0x9000
	s_movk_i32 s0, 0x180
	v_lshl_add_u64 v[184:185], v[194:195], 0, s[2:3]
	v_lshl_add_u64 v[180:181], v[196:197], 0, s[2:3]
	v_lshl_add_u64 v[176:177], v[198:199], 0, s[0:1]
	global_load_dwordx4 v[184:187], v[184:185], off
	global_load_dwordx4 v[180:183], v[180:181], off
	global_load_dwordx4 v[176:179], v[176:177], off
	v_readfirstlane_b32 s0, v204
	s_nop 3
	s_lshr_b32 s0, s0, 8
	s_cmp_lg_u32 s0, 0
	s_cbranch_scc0 .Lmla_noprio
	s_setprio 1
.Lmla_noprio:
	s_waitcnt lgkmcnt(0)
	s_barrier
	ds_read_b128 v[222:225], v220
	ds_read_b128 v[226:229], v220 offset:6656
	ds_read_b128 v[230:233], v220 offset:32
	ds_read_b128 v[234:237], v220 offset:6688

.Lmla_skipB:
	v_mfma_f32_32x32x16_bf16 v[48:63], v[234:237], v[120:123], v[48:63]
	ds_read_b128 v[234:237], v220 offset:6688
	s_add_i32 s10, s10, 1
	s_cmp_eq_u32 s10, 3
	s_cselect_b32 s10, 0, s10
	s_add_i32 s9, s9, 1
	s_cmpk_lg_i32 s9, 0x81
	s_cbranch_scc1 .Lmla_loop
	s_waitcnt lgkmcnt(0)
	v_exp_f32_e32 v80, v80
	v_exp_f32_e32 v81, v81
	v_exp_f32_e32 v82, v82
	v_exp_f32_e32 v83, v83
	v_exp_f32_e32 v84, v84
	v_exp_f32_e32 v85, v85
	v_exp_f32_e32 v86, v86
	v_exp_f32_e32 v87, v87
	v_exp_f32_e32 v88, v88
	v_add_f32_e32 v201, v201, v80
	v_exp_f32_e32 v89, v89
	v_add_f32_e32 v201, v201, v81
	v_exp_f32_e32 v90, v90
	v_add_f32_e32 v201, v201, v82
	v_exp_f32_e32 v91, v91
	v_add_f32_e32 v201, v201, v83
	v_exp_f32_e32 v92, v92
	v_add_f32_e32 v201, v201, v84
	v_exp_f32_e32 v93, v93
	v_add_f32_e32 v201, v201, v85
	v_exp_f32_e32 v94, v94
	v_add_f32_e32 v201, v201, v86
	v_exp_f32_e32 v95, v95
	v_add_f32_e32 v201, v201, v87
	v_cvt_pk_bf16_f32 v80, v80, v81
	v_cvt_pk_bf16_f32 v81, v82, v83
	v_cvt_pk_bf16_f32 v82, v84, v85
	v_cvt_pk_bf16_f32 v83, v86, v87
	v_exp_f32_e32 v96, v96
	v_add_f32_e32 v201, v201, v88
	v_exp_f32_e32 v97, v97
	v_add_f32_e32 v201, v201, v89
	v_exp_f32_e32 v98, v98
	v_add_f32_e32 v201, v201, v90
	v_exp_f32_e32 v99, v99
	v_add_f32_e32 v201, v201, v91
	v_exp_f32_e32 v100, v100
	v_add_f32_e32 v201, v201, v92
	v_exp_f32_e32 v101, v101
	v_add_f32_e32 v201, v201, v93
	v_exp_f32_e32 v102, v102
	v_add_f32_e32 v201, v201, v94
	v_exp_f32_e32 v103, v103
	v_add_f32_e32 v201, v201, v95
	v_cvt_pk_bf16_f32 v88, v88, v89
	v_cvt_pk_bf16_f32 v89, v90, v91
	v_cvt_pk_bf16_f32 v90, v92, v93
	v_cvt_pk_bf16_f32 v91, v94, v95
	v_exp_f32_e32 v104, v104
	v_add_f32_e32 v201, v201, v96
	v_exp_f32_e32 v105, v105
	v_add_f32_e32 v201, v201, v97
	v_exp_f32_e32 v106, v106
	v_add_f32_e32 v201, v201, v98
	v_exp_f32_e32 v107, v107
	v_add_f32_e32 v201, v201, v99
	v_exp_f32_e32 v108, v108
	v_add_f32_e32 v201, v201, v100
	v_exp_f32_e32 v109, v109
	v_add_f32_e32 v201, v201, v101
	v_exp_f32_e32 v110, v110
	v_add_f32_e32 v201, v201, v102
	v_exp_f32_e32 v111, v111
	v_add_f32_e32 v201, v201, v103
	v_cvt_pk_bf16_f32 v96, v96, v97
	v_cvt_pk_bf16_f32 v97, v98, v99
	v_cvt_pk_bf16_f32 v98, v100, v101
	v_cvt_pk_bf16_f32 v99, v102, v103
	v_add_f32_e32 v201, v201, v104
	v_add_f32_e32 v201, v201, v105
	v_add_f32_e32 v201, v201, v106
	v_add_f32_e32 v201, v201, v107
	v_add_f32_e32 v201, v201, v108
	v_add_f32_e32 v201, v201, v109
	v_add_f32_e32 v201, v201, v110
	v_add_f32_e32 v201, v201, v111
	v_cvt_pk_bf16_f32 v104, v104, v105
	v_cvt_pk_bf16_f32 v105, v106, v107
	v_cvt_pk_bf16_f32 v106, v108, v109
	v_cvt_pk_bf16_f32 v107, v110, v111
	ds_read_b128 v[222:225], v221 offset:64
	ds_read_b128 v[226:229], v221 offset:4672
	ds_read_b128 v[230:233], v221 offset:96
	ds_read_b128 v[234:237], v221 offset:4704
	s_waitcnt lgkmcnt(3)
	v_mfma_f32_32x32x16_bf16 v[0:15], v[222:225], v[80:83], v[0:15]
	ds_read_b128 v[222:225], v221
	s_waitcnt lgkmcnt(3)
	v_mfma_f32_32x32x16_bf16 v[16:31], v[226:229], v[80:83], v[16:31]
	ds_read_b128 v[226:229], v221 offset:4608
	s_waitcnt lgkmcnt(3)
	v_mfma_f32_32x32x16_bf16 v[0:15], v[230:233], v[88:91], v[0:15]
	ds_read_b128 v[230:233], v221 offset:32
	s_waitcnt lgkmcnt(3)
	v_mfma_f32_32x32x16_bf16 v[16:31], v[234:237], v[88:91], v[16:31]
	ds_read_b128 v[234:237], v221 offset:4640
	s_waitcnt lgkmcnt(3)
	v_mfma_f32_32x32x16_bf16 v[0:15], v[222:225], v[96:99], v[0:15]
	s_waitcnt lgkmcnt(2)
	v_mfma_f32_32x32x16_bf16 v[16:31], v[226:229], v[96:99], v[16:31]
	s_waitcnt lgkmcnt(1)
	v_mfma_f32_32x32x16_bf16 v[0:15], v[230:233], v[104:107], v[0:15]
	s_waitcnt lgkmcnt(0)
	v_mfma_f32_32x32x16_bf16 v[16:31], v[234:237], v[104:107], v[16:31]
	s_setprio 0
	s_barrier
	s_branch .LBB0_216
